# global attention: per-step row-max chain removed; rescale check moved after the step using the step row sums (lazy rebase of m_ref), exact f32 softmax math unchanged
# speedup vs baseline: 1.0174x; 1.0174x over previous
; #define LAS __attribute__((address_space(3)))
; DI int get_tid() { int t = threadIdx.x; asm volatile("" : "+v"(t)); return t; }
; DI float opaque0() { float z; asm volatile("v_mov_b32 %0, 0" : "=v"(z)); return z; }
; template <bool MASKED> ...
;     const int tid = get_tid(), lane = tid & 63, wave = tid >> 6, l31 = lane & 31, h = lane >> 5;
;     const int ntiles = nlat + nctx;
;     bf16x8 qf[2][4];
; #pragma unroll
;     for (int q = 0; q < 2; ++q) {
;         const bf16_t* qp = Qb + (size_t)(qrow0 + wave * 64 + q * 32 + l31) * ldq + qcol + 8 * h;
; #pragma unroll
;         for (int ks = 0; ks < 4; ++ks) qf[q][ks] = *(const bf16x8*)(qp + 16 * ks);
;     }
;     const int lrow = tid >> 3, lkc = tid & 7;
;     auto tile_off = [&](int i) -> size_t {
;         const int r0 = (i < nlat) ? (lat_row0 + 64 * i) : (ctx_row0 + 64 * (i - nlat));
;         return (size_t)(r0 + lrow) * ldkv + kvcol + lkc * 8;
;     };
;     lchar* const Kbase = lds; lchar* const Vbase = lds + 2 * KV_K;
;     constexpr int VB = 64 * VSTR;
;     const int koff = lrow * KSTR + lkc * 16, voff = lrow * VSTR + lkc * 16;
;     f32x16 o[2][2];
;     { const float z0 = opaque0();
; #pragma unroll
;       for (int q = 0; q < 2; ++q)
; #pragma unroll
;         for (int dt = 0; dt < 2; ++dt)
; #pragma unroll
;             for (int i = 0; i < 16; ++i) o[q][dt][i] = z0; }
;     float m_ref[2] = {0.f, 0.f}, lsum[2] = {0.f, 0.f};
;     const int qw0 = __builtin_amdgcn_readfirstlane(qpos0 + wave * 64);
;     u32x4 rk, rv;
;     {
;         const u32x4 k0 = *(const u32x4*)(Kb + tile_off(0)), v0 = *(const u32x4*)(Vb + tile_off(0));
;         rk = *(const u32x4*)(Kb + tile_off(1)); rv = *(const u32x4*)(Vb + tile_off(1));
;         *(LAS u32x4*)(Kbase + koff) = k0; *(LAS u32x4*)(Vbase + voff) = v0;
;     }
;     __syncthreads();
;     {
;         *(LAS u32x4*)(Kbase + KV_K + koff) = rk; *(LAS u32x4*)(Vbase + VB + voff) = rv;
;         rk = *(const u32x4*)(Kb + tile_off(2)); rv = *(const u32x4*)(Vb + tile_off(2));
;         attn2_step<true, MASKED>(o, m_ref, lsum, qf, Kbase, Vbase, lane, kpos0, qw0, m_init, l0);
.LBB0_188:
	s_and_b64 vcc, exec, s[0:1]
	s_cbranch_vccz .LBB0_175
	v_readlane_b32 s22, v254, 20
	v_readlane_b32 s23, v254, 21
	s_mov_b64 s[0:1], -1
	s_and_b64 vcc, exec, s[22:23]
	s_cbranch_vccz .LBB0_195
	s_bfe_u32 s26, s31, 0x20005
	s_lshl_b32 s1, s31, 6
	s_ashr_i32 s2, s31, 7
	s_lshl_b32 s0, s26, 8
	s_and_b32 s1, s1, 0xc0
	s_lshl_b32 s22, s31, 7
	s_or_b32 s0, s0, s1
	s_lshl_b32 s1, s2, 12
	s_and_b32 s22, s22, 0xe00
	v_mov_b32_e32 v98, v171
	s_or_b32 s22, s1, s22
	s_lshl_b32 s2, s2, 8
	s_add_i32 s2, s2, 0x10000
	v_and_b32_e32 v0, 0xffffffc0, v98
	v_add_u32_e32 v0, s22, v0
	s_lshl_b32 s22, s0, 1
	v_readlane_b32 s36, v254, 48
	v_bfe_u32 v99, v98, 5, 1
	v_readlane_b32 s37, v254, 49
	s_add_u32 s22, s36, s22
	s_waitcnt vmcnt(0)
	v_and_b32_e32 v32, 31, v98
	s_addc_u32 s23, s37, 0
	v_lshlrev_b32_e32 v128, 4, v99
	v_or_b32_e32 v174, v0, v32
	v_lshl_add_u64 v[0:1], s[22:23], 0, v[128:129]
	v_readlane_b32 s22, v254, 46
	v_readlane_b32 s23, v254, 47
	s_mov_b32 s36, s22
	v_mad_i64_i32 v[2:3], s[22:23], s36, v174, 0
	v_lshl_add_u64 v[2:3], v[2:3], 1, v[0:1]
	v_or_b32_e32 v172, 32, v174
	v_ashrrev_i32_e32 v188, 3, v98
	global_load_dwordx4 v[130:133], v[2:3], off
	global_load_dwordx4 v[134:137], v[2:3], off offset:32
	global_load_dwordx4 v[138:141], v[2:3], off offset:64
	global_load_dwordx4 v[142:145], v[2:3], off offset:96
	v_mad_i64_i32 v[2:3], s[22:23], s36, v172, 0
	v_add_u32_e32 v33, s1, v188
	v_lshl_add_u64 v[0:1], v[2:3], 1, v[0:1]
	v_mad_i64_i32 v[16:17], s[22:23], s30, v33, 0
	v_readlane_b32 s40, v252, 47
	global_load_dwordx4 v[146:149], v[0:1], off
	global_load_dwordx4 v[150:153], v[0:1], off offset:32
	global_load_dwordx4 v[154:157], v[0:1], off offset:64
	global_load_dwordx4 v[158:161], v[0:1], off offset:96
	v_lshlrev_b32_e32 v0, 4, v98
	v_lshlrev_b64 v[20:21], 1, v[16:17]
	v_readlane_b32 s41, v252, 48
	v_readlane_b32 s36, v252, 31
	v_and_b32_e32 v96, 0x70, v0
	s_movk_i32 s27, 0x90
	v_lshl_add_u64 v[16:17], s[40:41], 0, v[20:21]
	v_readlane_b32 s37, v252, 32
	s_lshl_b32 s36, s26, 7
	v_mad_u64_u32 v[176:177], s[22:23], v188, s27, v[96:97]
	v_lshl_add_u64 v[16:17], v[16:17], 0, s[36:37]
	v_mov_b32_e32 v97, v129
	v_lshl_add_u64 v[16:17], v[16:17], 0, v[96:97]
	v_add_u32_e32 v24, 64, v33
	v_mov_b32 v0, 0
	global_load_dwordx4 v[16:19], v[16:17], off
	v_mad_i64_i32 v[24:25], s[22:23], s30, v24, 0
	v_lshlrev_b64 v[28:29], 1, v[24:25]
	v_lshl_add_u64 v[20:21], s[38:39], 0, v[20:21]
	v_lshl_add_u64 v[24:25], s[40:41], 0, v[28:29]
	v_lshl_add_u64 v[20:21], v[20:21], 0, s[36:37]
	v_lshl_add_u64 v[24:25], v[24:25], 0, s[36:37]
	v_lshl_add_u64 v[28:29], s[38:39], 0, v[28:29]
	v_lshl_add_u64 v[20:21], v[20:21], 0, v[96:97]
	v_lshl_add_u64 v[24:25], v[24:25], 0, v[96:97]
	v_lshl_add_u64 v[28:29], v[28:29], 0, s[36:37]
	global_load_dwordx4 v[20:23], v[20:21], off
	v_lshl_add_u64 v[28:29], v[28:29], 0, v[96:97]
	global_load_dwordx4 v[24:27], v[24:25], off
	v_mad_u64_u32 v[178:179], s[22:23], v188, 48, v[176:177]
	global_load_dwordx4 v[28:31], v[28:29], off
	v_and_b32_e32 v80, 63, v98
	v_mul_u32_u24_e32 v179, 0x90, v32
	v_cmp_gt_u32_e32 vcc, 32, v80
	v_lshlrev_b32_e32 v190, 2, v99
	v_mov_b32_e32 v1, v0
	v_mov_b32_e32 v2, v0
	v_mov_b32_e32 v3, v0
	v_mov_b32_e32 v4, v0
	v_mov_b32_e32 v5, v0
	v_mov_b32_e32 v6, v0
	v_mov_b32_e32 v7, v0
	v_mov_b32_e32 v8, v0
	v_mov_b32_e32 v9, v0
	v_mov_b32_e32 v10, v0
	v_mov_b32_e32 v11, v0
	v_mov_b32_e32 v12, v0
	v_mov_b32_e32 v13, v0
	v_mov_b32_e32 v14, v0
	v_mov_b32_e32 v15, v0
	s_add_u32 s26, s40, s36
	v_ashrrev_i32_e32 v175, 31, v174
	v_ashrrev_i32_e32 v173, 31, v172
	s_waitcnt vmcnt(0)
	ds_write_b128 v176, v[16:19]
	v_add_u32_e32 v16, 0x80, v33
	v_mad_i64_i32 v[16:17], s[22:23], s30, v16, 0
	v_lshlrev_b64 v[16:17], 1, v[16:17]
	v_lshl_add_u64 v[18:19], s[40:41], 0, v[16:17]
	v_lshl_add_u64 v[16:17], s[38:39], 0, v[16:17]
	v_lshl_add_u64 v[18:19], v[18:19], 0, s[36:37]
	v_lshl_add_u64 v[16:17], v[16:17], 0, s[36:37]
	v_lshl_add_u64 v[18:19], v[18:19], 0, v[96:97]
	v_lshl_add_u64 v[16:17], v[16:17], 0, v[96:97]
	s_mov_b32 s23, 0xf149f2ca
	ds_write_b128 v178, v[20:23] offset:18432
	s_waitcnt lgkmcnt(0)
	s_barrier
	ds_write_b128 v176, v[24:27] offset:9216
	ds_write_b128 v178, v[28:31] offset:30720
	global_load_dwordx4 v[162:165], v[18:19], off
	global_load_dwordx4 v[166:169], v[16:17], off
	v_mad_u32_u24 v16, v32, s27, v128
	v_or_b32_e32 v17, 32, v80
	v_mul_u32_u24_e32 v189, 0x90, v17
	v_mad_u32_u24 v17, v17, s27, v128
	ds_read_b128 v[82:85], v16
	ds_read_b128 v[86:89], v16 offset:32
	ds_read_b128 v[90:93], v17
	ds_read_b128 v[100:103], v17 offset:32
	ds_read_b128 v[104:107], v16 offset:64
	ds_read_b128 v[108:111], v17 offset:64
	ds_read_b128 v[112:115], v16 offset:96
	ds_read_b128 v[116:119], v17 offset:96
	v_mov_b32 v32, 0
	v_mov_b32 v16, 0
	s_addc_u32 s27, s41, 0
	v_mov_b32_e32 v33, v32
	v_mov_b32_e32 v34, v32
	v_mov_b32_e32 v35, v32
	v_mov_b32_e32 v36, v32
	v_mov_b32_e32 v37, v32
	v_mov_b32_e32 v38, v32
	v_mov_b32_e32 v39, v32
	v_mov_b32_e32 v40, v32
	v_mov_b32_e32 v41, v32
	v_mov_b32_e32 v42, v32
	v_mov_b32_e32 v43, v32
	v_mov_b32_e32 v44, v32
	v_mov_b32_e32 v45, v32
	v_mov_b32_e32 v46, v32
	v_mov_b32_e32 v47, v32
	v_mov_b32_e32 v17, v16
	v_mov_b32_e32 v18, v16
	s_waitcnt lgkmcnt(7)
	v_mfma_f32_32x32x16_bf16 v[64:79], v[82:85], v[130:133], v[32:47]
	v_mov_b32_e32 v19, v16
	v_mov_b32_e32 v20, v16
	v_mov_b32_e32 v21, v16
	v_mov_b32_e32 v22, v16
	v_mov_b32_e32 v23, v16
	v_mov_b32_e32 v24, v16
	v_mov_b32_e32 v25, v16
	s_waitcnt lgkmcnt(5)
; #define LAS __attribute__((address_space(3)))
; DI float shx(float v, int k, int lane) { return __builtin_bit_cast(float, __builtin_amdgcn_ds_bpermute((lane ^ k) << 2, __builtin_bit_cast(int, v))); }
; DI int crow(int i, int h) { return (i & 3) + 8 * (i >> 2) + 4 * h; }
; #define MFMA32(a, b, c) __builtin_amdgcn_mfma_f32_32x32x16_bf16((a), (b), (c), 0, 0, 0)
; DI float opaque0() { float z; asm volatile("v_mov_b32 %0, 0" : "=v"(z)); return z; }
; template <bool FIRST, bool MASKED>
; DI void attn2_step(f32x16 (&o)[2][2], float (&m_ref)[2], float (&lsum)[2], const bf16x8 (&qf)[2][4], const lchar* Kl, const lchar* Vl, int lane, int kp0, int qw0, float m_init, float l0) {
;     ...
;     bf16x8 kf[4][2];
; #pragma unroll
;     for (int ks = 0; ks < 4; ++ks)
; #pragma unroll
;         for (int kt = 0; kt < 2; ++kt) kf[ks][kt] = *(const LAS bf16x8*)(Kl + (32 * kt + l31) * KSTR + ks * 32 + h * 16);
;     f32x16 sc[2][2];
; #pragma unroll
;     for (int q = 0; q < 2; ++q) {
;         const float init = FIRST ? opaque0() : -m_ref[q];
; #pragma unroll
;         for (int kt = 0; kt < 2; ++kt)
; #pragma unroll
;             for (int i = 0; i < 16; ++i) sc[q][kt][i] = init;
; #pragma unroll
;         for (int ks = 0; ks < 4; ++ks)
; #pragma unroll
;             for (int kt = 0; kt < 2; ++kt) sc[q][kt] = MFMA32(kf[ks][kt], qf[q][ks], sc[q][kt]);
;     }
;     if (MASKED && kp0 >= 0 && !(kp0 >= qw0 + 63 - 128 && kp0 + 63 <= qw0 + 128)) {
; #pragma unroll
;         for (int q = 0; q < 2; ++q) {
;             const int qpos = qw0 + q * 32 + l31;
; #pragma unroll
;             for (int kt = 0; kt < 2; ++kt)
; #pragma unroll
;                 for (int i = 0; i < 16; ++i) {
;                     const int diff = qpos - (kp0 + 32 * kt + crow(i, h));
;                     if (diff > 128 || diff < -128) sc[q][kt][i] = -1e30f;
;                 }
;         }
;     }
;     float mx[2];
; #pragma unroll
;     for (int q = 0; q < 2; ++q) {
;         float m = fmaxf(sc[q][0][0], sc[q][1][0]);
; #pragma unroll
;         for (int i = 1; i < 16; ++i) m = fmaxf(m, fmaxf(sc[q][0][i], sc[q][1][i]));
;         mx[q] = fmaxf(m, shx(m, 32, lane));
;     }
;     if (FIRST) {
; #pragma unroll
;         for (int q = 0; q < 2; ++q) {
;             m_ref[q] = fmaxf(m_init, mx[q]);
	v_mfma_f32_32x32x16_bf16 v[32:47], v[90:93], v[130:133], v[32:47]
	v_mov_b32_e32 v26, v16
	v_mov_b32_e32 v27, v16
	v_mov_b32_e32 v28, v16
	v_mov_b32_e32 v29, v16
	v_mov_b32_e32 v30, v16
	v_mov_b32_e32 v31, v16
	v_lshl_add_u64 v[184:185], s[26:27], 0, v[96:97]
	v_mfma_f32_32x32x16_bf16 v[64:79], v[86:89], v[134:137], v[64:79]
	v_writelane_b32 v252, s36, 31
	s_add_u32 s26, s38, s36
	s_addc_u32 s27, s39, 0
	s_mov_b32 s22, 2
	v_writelane_b32 v252, s37, 32
	v_lshl_add_u64 v[186:187], s[26:27], 0, v[96:97]
	s_waitcnt lgkmcnt(4)
	v_mfma_f32_32x32x16_bf16 v[32:47], v[100:103], v[134:137], v[32:47]
	s_waitcnt lgkmcnt(3)
	v_mfma_f32_32x32x16_bf16 v[64:79], v[104:107], v[138:141], v[64:79]
	s_waitcnt lgkmcnt(2)
	v_mfma_f32_32x32x16_bf16 v[32:47], v[108:111], v[138:141], v[32:47]
	v_mfma_f32_32x32x16_bf16 v[48:63], v[82:85], v[146:149], v[16:31]
	v_mfma_f32_32x32x16_bf16 v[16:31], v[90:93], v[146:149], v[16:31]
	s_waitcnt lgkmcnt(1)
	v_mfma_f32_32x32x16_bf16 v[64:79], v[112:115], v[142:145], v[64:79]
	s_waitcnt lgkmcnt(0)
	v_mfma_f32_32x32x16_bf16 v[32:47], v[116:119], v[142:145], v[32:47]
	s_nop 9
	v_max_f32_e32 v82, v65, v65
	v_max_f32_e32 v83, v66, v66
	v_max_f32_e32 v84, v67, v67
	v_mfma_f32_32x32x16_bf16 v[48:63], v[86:89], v[150:153], v[48:63]
	v_max_f32_e32 v81, v33, v33
	v_max_f32_e32 v81, v82, v81
	v_max_f32_e32 v82, v34, v34
	v_max_f32_e32 v82, v83, v82
	v_max_f32_e32 v83, v35, v35
	v_max3_f32 v81, v64, v32, v81
	v_max_f32_e32 v83, v84, v83
	v_mfma_f32_32x32x16_bf16 v[16:31], v[100:103], v[150:153], v[16:31]
	v_max3_f32 v81, v81, v82, v83
	v_max_f32_e32 v82, v36, v36
	v_max_f32_e32 v83, v68, v68
	v_max_f32_e32 v82, v83, v82
	v_max_f32_e32 v83, v37, v37
	v_max_f32_e32 v84, v69, v69
	v_max_f32_e32 v83, v84, v83
	v_mfma_f32_32x32x16_bf16 v[48:63], v[104:107], v[154:157], v[48:63]
	v_max3_f32 v81, v81, v82, v83
	v_max_f32_e32 v82, v38, v38
	v_max_f32_e32 v83, v70, v70
	v_max_f32_e32 v82, v83, v82
	v_max_f32_e32 v83, v39, v39
	v_max_f32_e32 v84, v71, v71
	v_max_f32_e32 v83, v84, v83
	v_mfma_f32_32x32x16_bf16 v[16:31], v[108:111], v[154:157], v[16:31]
	v_max3_f32 v81, v81, v82, v83
	v_max_f32_e32 v82, v40, v40
	v_max_f32_e32 v83, v72, v72
	v_max_f32_e32 v82, v83, v82
	v_max_f32_e32 v83, v41, v41
	v_max_f32_e32 v84, v73, v73
	v_max_f32_e32 v83, v84, v83
	v_max3_f32 v81, v81, v82, v83
	v_max_f32_e32 v82, v42, v42
	v_max_f32_e32 v83, v74, v74
	v_mfma_f32_32x32x16_bf16 v[48:63], v[112:115], v[158:161], v[48:63]
	v_max_f32_e32 v82, v83, v82
	v_max_f32_e32 v83, v43, v43
	v_max_f32_e32 v84, v75, v75
	v_max_f32_e32 v83, v84, v83
	v_max3_f32 v81, v81, v82, v83
	v_max_f32_e32 v82, v44, v44
	v_max_f32_e32 v83, v76, v76
	v_mfma_f32_32x32x16_bf16 v[16:31], v[116:119], v[158:161], v[16:31]
	v_max_f32_e32 v82, v83, v82
	v_max_f32_e32 v83, v45, v45
	v_max_f32_e32 v84, v77, v77
	v_max_f32_e32 v83, v84, v83
	v_max3_f32 v81, v81, v82, v83
	v_max_f32_e32 v82, v46, v46
	v_max_f32_e32 v83, v78, v78
	v_max_f32_e32 v82, v83, v82
	v_max_f32_e32 v83, v47, v47
	v_max_f32_e32 v84, v79, v79
	v_max_f32_e32 v83, v84, v83
	v_max3_f32 v81, v81, v82, v83
	v_max_f32_e32 v83, v17, v17
	v_max_f32_e32 v84, v49, v49
	v_max_f32_e32 v83, v84, v83
	v_max_f32_e32 v84, v18, v18
	v_max_f32_e32 v85, v50, v50
	v_max_f32_e32 v84, v85, v84
	v_max_f32_e32 v85, v19, v19
	v_max_f32_e32 v86, v51, v51
	v_max3_f32 v83, v48, v16, v83
	v_max_f32_e32 v85, v86, v85
	v_max3_f32 v83, v83, v84, v85
	v_max_f32_e32 v84, v20, v20
	v_max_f32_e32 v85, v52, v52
	v_max_f32_e32 v84, v85, v84
	v_max_f32_e32 v85, v21, v21
	v_max_f32_e32 v86, v53, v53
	v_max_f32_e32 v85, v86, v85
	v_max3_f32 v83, v83, v84, v85
	v_max_f32_e32 v84, v22, v22
	v_max_f32_e32 v85, v54, v54
	v_max_f32_e32 v84, v85, v84
	v_max_f32_e32 v85, v23, v23
	v_max_f32_e32 v86, v55, v55
	v_max_f32_e32 v85, v86, v85
	v_max3_f32 v83, v83, v84, v85
	v_max_f32_e32 v84, v24, v24
	v_max_f32_e32 v85, v56, v56
	v_max_f32_e32 v84, v85, v84
	v_max_f32_e32 v85, v25, v25
	v_max_f32_e32 v86, v57, v57
	v_max_f32_e32 v85, v86, v85
	v_max3_f32 v83, v83, v84, v85
	v_max_f32_e32 v84, v26, v26
	v_max_f32_e32 v85, v58, v58
	v_max_f32_e32 v84, v85, v84
	v_max_f32_e32 v85, v27, v27
	v_max_f32_e32 v86, v59, v59
	v_max_f32_e32 v85, v86, v85
	v_max3_f32 v83, v83, v84, v85
	v_max_f32_e32 v84, v28, v28
	v_max_f32_e32 v85, v60, v60
	v_max_f32_e32 v84, v85, v84
	v_max_f32_e32 v85, v29, v29
	v_max_f32_e32 v86, v61, v61
	v_max_f32_e32 v85, v86, v85
	v_max3_f32 v83, v83, v84, v85
	v_max_f32_e32 v84, v30, v30
	v_max_f32_e32 v85, v62, v62
	v_max_f32_e32 v84, v85, v84
	v_max_f32_e32 v85, v31, v31
	v_max_f32_e32 v86, v63, v63
	v_lshlrev_b32_e32 v100, 2, v80
	v_max_f32_e32 v85, v86, v85
	v_xor_b32_e32 v177, 0x80, v100
	v_max3_f32 v83, v83, v84, v85
	ds_bpermute_b32 v82, v177, v81
	ds_bpermute_b32 v84, v177, v83
	s_waitcnt lgkmcnt(1)
	v_max3_f32 v181, v81, v82, s23
	s_waitcnt lgkmcnt(0)
; #define LAS __attribute__((address_space(3)))
; template <bool FIRST, bool MASKED>
; DI void attn2_step(f32x16 (&o)[2][2], float (&m_ref)[2], float (&lsum)[2], const bf16x8 (&qf)[2][4], const lchar* Kl, const lchar* Vl, int lane, int kp0, int qw0, float m_init, float l0) {
;     ...
;             m_ref[q] = fmaxf(m_init, mx[q]);
;             lsum[q] = (h == 0) ? l0 * fast_exp2(m_init - m_ref[q]) : 0.f;
; #pragma unroll
;             for (int kt = 0; kt < 2; ++kt)
; #pragma unroll
;                 for (int i = 0; i < 16; ++i) sc[q][kt][i] -= m_ref[q];
;         }
;     } else if (__builtin_amdgcn_ballot_w64(fmaxf(mx[0], mx[1]) > ATT_THR) != 0ull) {
; #pragma unroll
;         for (int q = 0; q < 2; ++q) {
;             const float delta = fmaxf(mx[q], 0.f), alpha = fast_exp2(-delta);
; #pragma unroll
;             for (int dt = 0; dt < 2; ++dt)
; #pragma unroll
;                 for (int i = 0; i < 16; ++i) o[q][dt][i] *= alpha;
;             lsum[q] *= alpha;
; #pragma unroll
;             for (int kt = 0; kt < 2; ++kt)
; #pragma unroll
;                 for (int i = 0; i < 16; ++i) sc[q][kt][i] -= delta;
;             m_ref[q] += delta;
;         }
;     }
;     bf16x8 pf[2][4];
; #pragma unroll
;     for (int q = 0; q < 2; ++q) {
;         float ps = 0.f;
; #pragma unroll
;         for (int kt = 0; kt < 2; ++kt)
; #pragma unroll
;             for (int i = 0; i < 16; ++i) { const float pv = fast_exp2(sc[q][kt][i]); sc[q][kt][i] = pv; ps += pv; }
;         lsum[q] += ps;
; #pragma unroll
;         for (int s = 0; s < 4; ++s) {
;             u32x4 w;
;             const int kt = s >> 1, b = 8 * (s & 1);
;             w.x = pack2(sc[q][kt][b + 0], sc[q][kt][b + 1]); w.y = pack2(sc[q][kt][b + 2], sc[q][kt][b + 3]);
;             w.z = pack2(sc[q][kt][b + 4], sc[q][kt][b + 5]); w.w = pack2(sc[q][kt][b + 6], sc[q][kt][b + 7]);
;             pf[q][s] = __builtin_bit_cast(bf16x8, w);
;         }
;     }
;     {
;         const int qq = (lane & 15) >> 2, pp = lane & 3, g16 = (lane >> 4) & 1;
;         const lchar* vb = Vl + (4 * h + qq) * VSTR + (16 * g16 + 4 * pp) * 2;
; #pragma unroll
;         for (int s = 0; s < 4; ++s)
; #pragma unroll
;             for (int dt = 0; dt < 2; ++dt) {
;                 const s16x4 lo = __builtin_amdgcn_ds_read_tr16_b64_v4i16((LAS s16x4*)(vb + (16 * s) * VSTR + dt * 64));
	v_max3_f32 v180, v83, v84, s23
	v_sub_f32_e32 v64, v64, v181
	v_sub_f32_e32 v48, v48, v180
	v_sub_f32_e32 v65, v65, v181
	v_sub_f32_e32 v92, v49, v180
	v_sub_f32_e32 v108, v16, v180
	v_sub_f32_e32 v110, v17, v180
	v_exp_f32_e32 v17, v64
	v_exp_f32_e32 v16, v48
	v_sub_f32_e32 v66, v66, v181
	v_sub_f32_e32 v50, v50, v180
	v_sub_f32_e32 v112, v18, v180
	v_sub_f32_e32 v114, v19, v180
	v_exp_f32_e32 v19, v65
	v_exp_f32_e32 v18, v92
	v_sub_f32_e32 v67, v67, v181
	v_sub_f32_e32 v93, v51, v180
	v_sub_f32_e32 v115, v20, v180
	v_sub_f32_e32 v116, v21, v180
	v_exp_f32_e32 v21, v66
	v_exp_f32_e32 v20, v50
	v_sub_f32_e32 v68, v68, v181
	v_sub_f32_e32 v76, v76, v181
	v_sub_f32_e32 v77, v77, v181
	v_sub_f32_e32 v52, v52, v180
	v_sub_f32_e32 v117, v22, v180
	v_sub_f32_e32 v118, v23, v180
	v_exp_f32_e32 v23, v67
	v_exp_f32_e32 v22, v93
	v_sub_f32_e32 v69, v69, v181
	v_sub_f32_e32 v87, v41, v181
	v_sub_f32_e32 v88, v43, v181
	v_sub_f32_e32 v94, v53, v180
	v_sub_f32_e32 v119, v24, v180
	v_sub_f32_e32 v120, v25, v180
	v_exp_f32_e32 v25, v68
	v_exp_f32_e32 v41, v76
	v_exp_f32_e32 v43, v77
	v_pk_add_f32 v[76:77], v[16:17], 0 op_sel_hi:[1,0]
	v_exp_f32_e32 v24, v52
	v_sub_f32_e32 v70, v70, v181
	v_sub_f32_e32 v54, v54, v180
	v_sub_f32_e32 v121, v26, v180
	v_sub_f32_e32 v122, v27, v180
	v_exp_f32_e32 v27, v69
	v_pk_add_f32 v[76:77], v[18:19], v[76:77]
	v_exp_f32_e32 v26, v94
	v_sub_f32_e32 v80, 0xf149f2ca, v181
	v_sub_f32_e32 v71, v71, v181
	v_sub_f32_e32 v95, v55, v180
	v_sub_f32_e32 v123, v28, v180
	v_sub_f32_e32 v124, v29, v180
	v_exp_f32_e32 v29, v70
	v_exp_f32_e32 v28, v54
	v_pk_add_f32 v[76:77], v[20:21], v[76:77]
	v_exp_f32_e32 v85, v80
	v_sub_f32_e32 v72, v72, v181
	v_sub_f32_e32 v32, v32, v181
	v_sub_f32_e32 v80, v33, v181
	v_sub_f32_e32 v33, 0xf149f2ca, v180
	v_sub_f32_e32 v56, v56, v180
	v_sub_f32_e32 v125, v30, v180
	v_sub_f32_e32 v126, v31, v180
	v_exp_f32_e32 v31, v71
	v_exp_f32_e32 v30, v95
	v_pk_add_f32 v[76:77], v[22:23], v[76:77]
	v_sub_f32_e32 v73, v73, v181
	v_sub_f32_e32 v34, v34, v181
	v_exp_f32_e32 v84, v33
	v_sub_f32_e32 v101, v57, v180
	v_exp_f32_e32 v33, v72
	v_exp_f32_e32 v49, v32
	v_exp_f32_e32 v32, v56
	v_pk_add_f32 v[76:77], v[24:25], v[76:77]
	v_sub_f32_e32 v74, v74, v181
	v_sub_f32_e32 v81, v35, v181
	v_sub_f32_e32 v36, v36, v181
	v_sub_f32_e32 v58, v58, v180
	v_exp_f32_e32 v35, v73
	v_exp_f32_e32 v53, v34
	v_exp_f32_e32 v34, v101
	v_pk_add_f32 v[76:77], v[26:27], v[76:77]
	v_sub_f32_e32 v75, v75, v181
	v_sub_f32_e32 v82, v37, v181
	v_sub_f32_e32 v38, v38, v181
	v_sub_f32_e32 v102, v59, v180
	v_exp_f32_e32 v37, v74
	v_exp_f32_e32 v57, v36
	v_exp_f32_e32 v36, v58
	v_pk_add_f32 v[76:77], v[28:29], v[76:77]
	v_sub_f32_e32 v86, v39, v181
	v_sub_f32_e32 v40, v40, v181
	v_sub_f32_e32 v60, v60, v180
	v_sub_f32_e32 v104, v61, v180
	v_exp_f32_e32 v39, v75
	v_exp_f32_e32 v61, v38
	v_exp_f32_e32 v38, v102
	v_pk_add_f32 v[76:77], v[30:31], v[76:77]
	v_sub_f32_e32 v42, v42, v181
	v_exp_f32_e32 v69, v40
	v_exp_f32_e32 v40, v60
	v_pk_add_f32 v[76:77], v[32:33], v[76:77]
	v_sub_f32_e32 v78, v78, v181
	v_sub_f32_e32 v44, v44, v181
	v_sub_f32_e32 v62, v62, v180
	v_exp_f32_e32 v103, v42
	v_pk_add_f32 v[76:77], v[34:35], v[76:77]
	v_exp_f32_e32 v42, v104
	v_sub_f32_e32 v79, v79, v181
	v_sub_f32_e32 v89, v45, v181
	v_sub_f32_e32 v46, v46, v181
	v_sub_f32_e32 v106, v63, v180
	v_exp_f32_e32 v45, v78
	v_exp_f32_e32 v107, v44
	v_pk_add_f32 v[76:77], v[36:37], v[76:77]
	v_exp_f32_e32 v44, v62
	v_sub_f32_e32 v90, v47, v181
	v_exp_f32_e32 v47, v79
	v_exp_f32_e32 v111, v46
	v_pk_add_f32 v[76:77], v[38:39], v[76:77]
	v_exp_f32_e32 v46, v106
	v_pk_add_f32 v[76:77], v[40:41], v[76:77]
	v_exp_f32_e32 v48, v108
	v_exp_f32_e32 v51, v80
	v_exp_f32_e32 v50, v110
	v_pk_add_f32 v[76:77], v[42:43], v[76:77]
	v_exp_f32_e32 v52, v112
	v_pk_add_f32 v[76:77], v[44:45], v[76:77]
	v_exp_f32_e32 v55, v81
	v_exp_f32_e32 v54, v114
	v_pk_add_f32 v[76:77], v[46:47], v[76:77]
	v_exp_f32_e32 v56, v115
	v_pk_add_f32 v[76:77], v[48:49], v[76:77]
	v_exp_f32_e32 v59, v82
	v_exp_f32_e32 v58, v116
	v_pk_add_f32 v[76:77], v[50:51], v[76:77]
	v_exp_f32_e32 v60, v117
	v_pk_add_f32 v[76:77], v[52:53], v[76:77]
	v_exp_f32_e32 v63, v86
	v_exp_f32_e32 v62, v118
	v_pk_add_f32 v[76:77], v[54:55], v[76:77]
	v_exp_f32_e32 v68, v119
	v_pk_add_f32 v[76:77], v[56:57], v[76:77]
	v_exp_f32_e32 v71, v87
	v_pk_add_f32 v[76:77], v[58:59], v[76:77]
	v_exp_f32_e32 v70, v120
	v_pk_add_f32 v[76:77], v[60:61], v[76:77]
	v_exp_f32_e32 v102, v121
	v_exp_f32_e32 v105, v88
	v_pk_add_f32 v[76:77], v[62:63], v[76:77]
	v_exp_f32_e32 v104, v122
	v_exp_f32_e32 v106, v123
	v_pk_add_f32 v[76:77], v[68:69], v[76:77]
	v_exp_f32_e32 v109, v89
	v_exp_f32_e32 v108, v124
	v_pk_add_f32 v[76:77], v[70:71], v[76:77]
	v_exp_f32_e32 v110, v125
	v_pk_add_f32 v[76:77], v[102:103], v[76:77]
	v_exp_f32_e32 v113, v90
	v_exp_f32_e32 v112, v126
	v_pk_add_f32 v[76:77], v[104:105], v[76:77]
	v_cvt_pk_bf16_f32 v92, v16, v18
	v_pk_add_f32 v[76:77], v[106:107], v[76:77]
	v_lshrrev_b32_e32 v16, 2, v98
	v_cvt_pk_bf16_f32 v88, v17, v19
	v_pk_add_f32 v[76:77], v[108:109], v[76:77]
	v_and_b32_e32 v17, 16, v98
	v_and_or_b32 v16, v16, 3, v190
	v_pk_mul_f32 v[78:79], v[84:85], 0 op_sel_hi:[1,0]
	v_pk_add_f32 v[76:77], v[110:111], v[76:77]
	v_mul_u32_u24_e32 v16, 0xc0, v16
	v_and_or_b32 v17, v100, 12, v17
	v_cndmask_b32_e32 v79, 0, v79, vcc
	v_cndmask_b32_e32 v78, 0, v78, vcc
	v_pk_add_f32 v[76:77], v[112:113], v[76:77]
	v_lshl_or_b32 v191, v17, 1, v16
	v_cvt_pk_bf16_f32 v72, v49, v51
	v_pk_add_f32 v[182:183], v[78:79], v[76:77]
	v_cvt_pk_bf16_f32 v76, v48, v50
	ds_read_b64_tr_b16 v[48:49], v191 offset:18432
	ds_read_b64_tr_b16 v[50:51], v191 offset:19968
	ds_read_b64_tr_b16 v[98:99], v191 offset:18496
	ds_read_b64_tr_b16 v[100:101], v191 offset:20032
	v_cvt_pk_bf16_f32 v89, v21, v23
	v_cvt_pk_bf16_f32 v90, v25, v27
	v_cvt_pk_bf16_f32 v91, v29, v31
	v_cvt_pk_bf16_f32 v93, v20, v22
	v_cvt_pk_bf16_f32 v94, v24, v26
	v_cvt_pk_bf16_f32 v95, v28, v30
	v_cvt_pk_bf16_f32 v80, v33, v35
	v_cvt_pk_bf16_f32 v81, v37, v39
	v_cvt_pk_bf16_f32 v82, v41, v43
	v_cvt_pk_bf16_f32 v83, v45, v47
	v_cvt_pk_bf16_f32 v84, v32, v34
	v_cvt_pk_bf16_f32 v85, v36, v38
	v_cvt_pk_bf16_f32 v86, v40, v42
	v_cvt_pk_bf16_f32 v87, v44, v46
	s_waitcnt lgkmcnt(2)
; #define LAS __attribute__((address_space(3)))
; #define MFMA32(a, b, c) __builtin_amdgcn_mfma_f32_32x32x16_bf16((a), (b), (c), 0, 0, 0)
; template <bool FIRST, bool MASKED>
; DI void attn2_step(f32x16 (&o)[2][2], float (&m_ref)[2], float (&lsum)[2], const bf16x8 (&qf)[2][4], const lchar* Kl, const lchar* Vl, int lane, int kp0, int qw0, float m_init, float l0) {
;     ...
;     {
;         const int qq = (lane & 15) >> 2, pp = lane & 3, g16 = (lane >> 4) & 1;
;         const lchar* vb = Vl + (4 * h + qq) * VSTR + (16 * g16 + 4 * pp) * 2;
; #pragma unroll
;         for (int s = 0; s < 4; ++s)
; #pragma unroll
;             for (int dt = 0; dt < 2; ++dt) {
;                 const s16x4 lo = __builtin_amdgcn_ds_read_tr16_b64_v4i16((LAS s16x4*)(vb + (16 * s) * VSTR + dt * 64));
;                 const s16x4 hi = __builtin_amdgcn_ds_read_tr16_b64_v4i16((LAS s16x4*)(vb + (16 * s + 8) * VSTR + dt * 64));
;                 const bf16x8 vf = __builtin_shufflevector(lo, hi, 0, 1, 2, 3, 4, 5, 6, 7);
; #pragma unroll
;                 for (int q = 0; q < 2; ++q) o[q][dt] = MFMA32(vf, pf[q][s], o[q][dt]);
;             }
;     }
; template <bool MASKED> ...
;     ...
;         __syncthreads();
	v_mfma_f32_32x32x16_bf16 v[32:47], v[48:51], v[88:91], v[0:15]
	v_cvt_pk_bf16_f32 v73, v53, v55
	v_cvt_pk_bf16_f32 v74, v57, v59
	v_cvt_pk_bf16_f32 v75, v61, v63
	v_cvt_pk_bf16_f32 v77, v52, v54
	v_cvt_pk_bf16_f32 v78, v56, v58
	v_cvt_pk_bf16_f32 v79, v60, v62
	v_cvt_pk_bf16_f32 v64, v69, v71
	v_mfma_f32_32x32x16_bf16 v[16:31], v[48:51], v[92:95], v[0:15]
	v_cvt_pk_bf16_f32 v65, v103, v105
	v_cvt_pk_bf16_f32 v66, v107, v109
	v_cvt_pk_bf16_f32 v67, v111, v113
	v_cvt_pk_bf16_f32 v68, v68, v70
	v_cvt_pk_bf16_f32 v69, v102, v104
	v_cvt_pk_bf16_f32 v70, v106, v108
	v_cvt_pk_bf16_f32 v71, v110, v112
	s_waitcnt lgkmcnt(0)
	v_mfma_f32_32x32x16_bf16 v[48:63], v[98:101], v[88:91], v[0:15]
	ds_read_b64_tr_b16 v[88:89], v191 offset:21504
	ds_read_b64_tr_b16 v[90:91], v191 offset:23040
	s_waitcnt lgkmcnt(0)
	v_mfma_f32_32x32x16_bf16 v[32:47], v[88:91], v[80:83], v[32:47]
	v_mfma_f32_32x32x16_bf16 v[16:31], v[88:91], v[84:87], v[16:31]
	ds_read_b64_tr_b16 v[88:89], v191 offset:21568
	ds_read_b64_tr_b16 v[90:91], v191 offset:23104
	v_mfma_f32_32x32x16_bf16 v[0:15], v[98:101], v[92:95], v[0:15]
	s_waitcnt lgkmcnt(0)
	v_mfma_f32_32x32x16_bf16 v[48:63], v[88:91], v[80:83], v[48:63]
	ds_read_b64_tr_b16 v[80:81], v191 offset:24576
	ds_read_b64_tr_b16 v[82:83], v191 offset:26112
	v_mfma_f32_32x32x16_bf16 v[0:15], v[88:91], v[84:87], v[0:15]
	s_waitcnt lgkmcnt(0)
	v_mfma_f32_32x32x16_bf16 v[32:47], v[80:83], v[72:75], v[32:47]
	v_mfma_f32_32x32x16_bf16 v[16:31], v[80:83], v[76:79], v[16:31]
	ds_read_b64_tr_b16 v[80:81], v191 offset:24640
	ds_read_b64_tr_b16 v[82:83], v191 offset:26176
	s_waitcnt lgkmcnt(0)
	v_mfma_f32_32x32x16_bf16 v[48:63], v[80:83], v[72:75], v[48:63]
	ds_read_b64_tr_b16 v[72:73], v191 offset:27648
	ds_read_b64_tr_b16 v[74:75], v191 offset:29184
	v_mfma_f32_32x32x16_bf16 v[0:15], v[80:83], v[76:79], v[0:15]
	s_waitcnt lgkmcnt(0)
	v_mfma_f32_32x32x16_bf16 v[32:47], v[72:75], v[64:67], v[32:47]
	v_mfma_f32_32x32x16_bf16 v[16:31], v[72:75], v[68:71], v[16:31]
	ds_read_b64_tr_b16 v[72:73], v191 offset:27712
	ds_read_b64_tr_b16 v[74:75], v191 offset:29248
	s_waitcnt lgkmcnt(0)
	s_barrier
	v_mfma_f32_32x32x16_bf16 v[48:63], v[72:75], v[64:67], v[48:63]
	v_mfma_f32_32x32x16_bf16 v[0:15], v[72:75], v[68:71], v[0:15]
	v_mov_b32_e32 v240, 0
	v_mov_b32_e32 v242, 0
	s_branch .LBB0_192

; template <bool FIRST, bool MASKED>
; DI void attn2_step(f32x16 (&o)[2][2], float (&m_ref)[2], float (&lsum)[2], const bf16x8 (&qf)[2][4], const lchar* Kl, const lchar* Vl, int lane, int kp0, int qw0, float m_init, float l0) {
;     ...
;     bf16x8 kf[4][2];
; #pragma unroll
;     for (int ks = 0; ks < 4; ++ks)
; #pragma unroll
;         for (int kt = 0; kt < 2; ++kt) kf[ks][kt] = *(const LAS bf16x8*)(Kl + (32 * kt + l31) * KSTR + ks * 32 + h * 16);
;     f32x16 sc[2][2];
; #pragma unroll
;     for (int q = 0; q < 2; ++q) {
;         const float init = FIRST ? opaque0() : -m_ref[q];
; #pragma unroll
;         for (int kt = 0; kt < 2; ++kt)
; #pragma unroll
;             for (int i = 0; i < 16; ++i) sc[q][kt][i] = init;
; #pragma unroll
;         for (int ks = 0; ks < 4; ++ks)
; #pragma unroll
;             for (int kt = 0; kt < 2; ++kt) sc[q][kt] = MFMA32(kf[ks][kt], qf[q][ks], sc[q][kt]);
;     }
;     if (MASKED && kp0 >= 0 && !(kp0 >= qw0 + 63 - 128 && kp0 + 63 <= qw0 + 128)) {
; #pragma unroll
;         for (int q = 0; q < 2; ++q) {
;             const int qpos = qw0 + q * 32 + l31;
; #pragma unroll
;             for (int kt = 0; kt < 2; ++kt)
; #pragma unroll
;                 for (int i = 0; i < 16; ++i) {
;                     const int diff = qpos - (kp0 + 32 * kt + crow(i, h));
;                     if (diff > 128 || diff < -128) sc[q][kt][i] = -1e30f;
;                 }
;         }
;     }
;     float mx[2];
; #pragma unroll
;     for (int q = 0; q < 2; ++q) {
;         float m = fmaxf(sc[q][0][0], sc[q][1][0]);
; #pragma unroll
;         for (int i = 1; i < 16; ++i) m = fmaxf(m, fmaxf(sc[q][0][i], sc[q][1][i]));
;         mx[q] = fmaxf(m, shx(m, 32, lane));
;     }
;     if (FIRST) {
; #pragma unroll
;         for (int q = 0; q < 2; ++q) {
;             m_ref[q] = fmaxf(m_init, mx[q]);
;             lsum[q] = (h == 0) ? l0 * fast_exp2(m_init - m_ref[q]) : 0.f;
; #pragma unroll
;             for (int kt = 0; kt < 2; ++kt)
; #pragma unroll
;                 for (int i = 0; i < 16; ++i) sc[q][kt][i] -= m_ref[q];
;         }
;     } else if (__builtin_amdgcn_ballot_w64(fmaxf(mx[0], mx[1]) > ATT_THR) != 0ull) {
; template <bool MASKED> ...
;     ...
;     for (int it = 1; it < ntiles; ++it) {
;         *(LAS u32x4*)(Kbase + ((it + 1) & 1) * KV_K + koff) = rk; *(LAS u32x4*)(Vbase + ((it + 1) & 1) * VB + voff) = rv;
;         const int i2 = min(it + 2, ntiles - 1);
.LBB0_192:
	s_and_b32 s26, s22, 1
	s_mul_i32 s27, s26, 0x2400
	s_add_i32 s23, s22, -1
	v_add_u32_e32 v64, s27, v176
	s_mulk_i32 s26, 0x3000
	s_waitcnt vmcnt(1)
	ds_write_b128 v64, v[162:165]
	v_add_u32_e32 v64, s26, v178
	s_min_i32 s26, s23, 0x41
	s_cmp_lt_u32 s23, 62
	s_cselect_b32 s27, 2, 0xffffffc2
	s_cselect_b32 s36, s1, s2
	s_and_b32 s23, s23, 1
	s_mul_i32 s37, s23, 0x2400
	s_waitcnt vmcnt(0)
	ds_write_b128 v64, v[166:169] offset:18432
	v_or_b32_e32 v64, s37, v128
	v_add_u32_e32 v65, v64, v179
	v_add_u32_e32 v64, v64, v189
	ds_read_b128 v[162:165], v65
	ds_read_b128 v[192:195], v65 offset:32
	ds_read_b128 v[208:211], v64
	ds_read_b128 v[212:215], v64 offset:32
	s_add_i32 s27, s27, s26
	v_xor_b32_e32 v80, 0x80000000, v181
	s_lshl_b32 s26, s27, 6
	v_mov_b32_e32 v81, v80
	v_mov_b64_e32 v[82:83], v[80:81]
	v_mov_b64_e32 v[84:85], v[80:81]
	v_mov_b64_e32 v[86:87], v[80:81]
	v_mov_b64_e32 v[88:89], v[80:81]
	v_mov_b64_e32 v[90:91], v[80:81]
	v_mov_b64_e32 v[92:93], v[80:81]
	v_mov_b64_e32 v[94:95], v[80:81]
	ds_read_b128 v[216:219], v65 offset:64
	ds_read_b128 v[220:223], v65 offset:96
	ds_read_b128 v[224:227], v64 offset:64
	ds_read_b128 v[228:231], v64 offset:96
	s_add_i32 s26, s26, s36
	v_xor_b32_e32 v64, 0x80000000, v180
	s_waitcnt lgkmcnt(7)
	v_mfma_f32_32x32x16_bf16 v[112:127], v[162:165], v[130:133], v[80:95]
	v_add_u32_e32 v166, s26, v188
	v_mov_b32_e32 v65, v64
	v_mov_b64_e32 v[66:67], v[64:65]
	v_mov_b64_e32 v[68:69], v[64:65]
	s_waitcnt lgkmcnt(5)
	v_mfma_f32_32x32x16_bf16 v[80:95], v[208:211], v[130:133], v[80:95]
	v_mov_b64_e32 v[70:71], v[64:65]
	v_mov_b64_e32 v[72:73], v[64:65]
	v_mov_b64_e32 v[74:75], v[64:65]
	v_mov_b64_e32 v[76:77], v[64:65]
	v_mov_b64_e32 v[78:79], v[64:65]
	v_mfma_f32_32x32x16_bf16 v[112:127], v[192:195], v[134:137], v[112:127]
	s_nop 0
	v_mfma_f32_32x32x16_bf16 v[96:111], v[162:165], v[146:149], v[64:79]
	v_mad_i64_i32 v[162:163], s[26:27], s30, v166, 0
	v_lshlrev_b64 v[162:163], 1, v[162:163]
	v_lshl_add_u64 v[164:165], v[184:185], 0, v[162:163]
	v_lshl_add_u64 v[166:167], v[186:187], 0, v[162:163]
	global_load_dwordx4 v[162:165], v[164:165], off
	s_nop 0
	global_load_dwordx4 v[166:169], v[166:167], off
	s_mov_b32 s26, 0x43800000
	s_waitcnt lgkmcnt(4)
	v_mfma_f32_32x32x16_bf16 v[80:95], v[212:215], v[134:137], v[80:95]
	s_waitcnt lgkmcnt(3)
	v_mfma_f32_32x32x16_bf16 v[112:127], v[216:219], v[138:141], v[112:127]
	s_waitcnt lgkmcnt(1)
	v_mfma_f32_32x32x16_bf16 v[80:95], v[224:227], v[138:141], v[80:95]
	v_mfma_f32_32x32x16_bf16 v[64:79], v[208:211], v[146:149], v[64:79]
	v_mfma_f32_32x32x16_bf16 v[112:127], v[220:223], v[142:145], v[112:127]
	s_waitcnt lgkmcnt(0)
	v_mfma_f32_32x32x16_bf16 v[80:95], v[228:231], v[142:145], v[80:95]
	v_mfma_f32_32x32x16_bf16 v[96:111], v[192:195], v[150:153], v[96:111]
	v_mfma_f32_32x32x16_bf16 v[64:79], v[212:215], v[150:153], v[64:79]
	v_mfma_f32_32x32x16_bf16 v[96:111], v[216:219], v[154:157], v[96:111]
	v_mfma_f32_32x32x16_bf16 v[64:79], v[224:227], v[154:157], v[64:79]
	v_mfma_f32_32x32x16_bf16 v[96:111], v[220:223], v[158:161], v[96:111]
	v_mfma_f32_32x32x16_bf16 v[64:79], v[228:231], v[158:161], v[64:79]
	s_mulk_i32 s23, 0x3000
	v_or_b32_e32 v244, s23, v191
	ds_read_b64_tr_b16 v[208:209], v244 offset:18432
	ds_read_b64_tr_b16 v[210:211], v244 offset:19968
	ds_read_b64_tr_b16 v[212:213], v244 offset:18496
	ds_read_b64_tr_b16 v[214:215], v244 offset:20032
	ds_read_b64_tr_b16 v[216:217], v244 offset:21504
	ds_read_b64_tr_b16 v[218:219], v244 offset:23040
	ds_read_b64_tr_b16 v[220:221], v244 offset:21568
	ds_read_b64_tr_b16 v[222:223], v244 offset:23104
	s_waitcnt lgkmcnt(0)
	ds_read_b64_tr_b16 v[224:225], v244 offset:24576
	ds_read_b64_tr_b16 v[226:227], v244 offset:26112
	ds_read_b64_tr_b16 v[228:229], v244 offset:24640
	ds_read_b64_tr_b16 v[230:231], v244 offset:26176
	ds_read_b64_tr_b16 v[232:233], v244 offset:27648
	ds_read_b64_tr_b16 v[234:235], v244 offset:29184
	ds_read_b64_tr_b16 v[236:237], v244 offset:27712
	ds_read_b64_tr_b16 v[238:239], v244 offset:29248
	v_max_f32_e32 v194, v240, v242
	v_cmp_lt_f32_e32 vcc, s26, v194
	s_cbranch_vccz .LBB0_191
; DI float fast_exp2(float x) { return __builtin_amdgcn_exp2f(x); }
; template <bool FIRST, bool MASKED>
; DI void attn2_step(f32x16 (&o)[2][2], float (&m_ref)[2], float (&lsum)[2], const bf16x8 (&qf)[2][4], const lchar* Kl, const lchar* Vl, int lane, int kp0, int qw0, float m_init, float l0) {
;     ...
;     } else if (__builtin_amdgcn_ballot_w64(fmaxf(mx[0], mx[1]) > ATT_THR) != 0ull) {
; #pragma unroll
;         for (int q = 0; q < 2; ++q) {
;             const float delta = fmaxf(mx[q], 0.f), alpha = fast_exp2(-delta);
; #pragma unroll
;             for (int dt = 0; dt < 2; ++dt)
; #pragma unroll
;                 for (int i = 0; i < 16; ++i) o[q][dt][i] *= alpha;
;             lsum[q] *= alpha;
; #pragma unroll
;             for (int kt = 0; kt < 2; ++kt)
; #pragma unroll
;                 for (int i = 0; i < 16; ++i) sc[q][kt][i] -= delta;
;             m_ref[q] += delta;
;         }
;     }
	s_nop 15
	v_log_f32_e32 v193, v240
	v_log_f32_e32 v192, v242
	s_nop 1
	v_mov_b32_e32 v194, v193
	v_mov_b32_e32 v195, v192
	s_nop 1
	v_permlane32_swap_b32_e32 v194, v193
	v_permlane32_swap_b32_e32 v195, v192
	s_nop 1
	v_max_f32_e32 v193, v193, v194
	v_max_f32_e32 v192, v192, v195
	v_max_f32_e32 v193, v193, v193
	v_max_f32_e32 v192, v192, v192
	v_max_f32_e32 v194, 0, v193
	v_max_f32_e32 v192, 0, v192
	v_exp_f32_e64 v196, -v194
	v_exp_f32_e64 v200, -v192
	v_pk_add_f32 v[96:97], v[96:97], v[192:193] op_sel_hi:[1,0] neg_lo:[0,1] neg_hi:[0,1]
	v_pk_add_f32 v[98:99], v[98:99], v[192:193] op_sel_hi:[1,0] neg_lo:[0,1] neg_hi:[0,1]
	v_pk_add_f32 v[100:101], v[100:101], v[192:193] op_sel_hi:[1,0] neg_lo:[0,1] neg_hi:[0,1]
	v_pk_mul_f32 v[30:31], v[30:31], v[200:201] op_sel_hi:[1,0]
	v_pk_mul_f32 v[28:29], v[28:29], v[200:201] op_sel_hi:[1,0]
	v_pk_mul_f32 v[26:27], v[26:27], v[200:201] op_sel_hi:[1,0]
	v_pk_mul_f32 v[24:25], v[24:25], v[200:201] op_sel_hi:[1,0]
	v_pk_mul_f32 v[22:23], v[22:23], v[200:201] op_sel_hi:[1,0]
	v_pk_mul_f32 v[20:21], v[20:21], v[200:201] op_sel_hi:[1,0]
	v_pk_mul_f32 v[18:19], v[18:19], v[200:201] op_sel_hi:[1,0]
	v_pk_mul_f32 v[16:17], v[16:17], v[200:201] op_sel_hi:[1,0]
	v_pk_mul_f32 v[14:15], v[14:15], v[200:201] op_sel_hi:[1,0]
	v_pk_mul_f32 v[12:13], v[12:13], v[200:201] op_sel_hi:[1,0]
	v_pk_mul_f32 v[10:11], v[10:11], v[200:201] op_sel_hi:[1,0]
	v_pk_mul_f32 v[8:9], v[8:9], v[200:201] op_sel_hi:[1,0]
	v_pk_mul_f32 v[6:7], v[6:7], v[200:201] op_sel_hi:[1,0]
	v_pk_mul_f32 v[4:5], v[4:5], v[200:201] op_sel_hi:[1,0]
	v_pk_mul_f32 v[2:3], v[2:3], v[200:201] op_sel_hi:[1,0]
	v_pk_mul_f32 v[0:1], v[0:1], v[200:201] op_sel_hi:[1,0]
	v_mov_b32_e32 v201, v196
	v_pk_add_f32 v[102:103], v[102:103], v[192:193] op_sel_hi:[1,0] neg_lo:[0,1] neg_hi:[0,1]
	v_pk_add_f32 v[104:105], v[104:105], v[192:193] op_sel_hi:[1,0] neg_lo:[0,1] neg_hi:[0,1]
	v_pk_add_f32 v[106:107], v[106:107], v[192:193] op_sel_hi:[1,0] neg_lo:[0,1] neg_hi:[0,1]
	v_pk_add_f32 v[108:109], v[108:109], v[192:193] op_sel_hi:[1,0] neg_lo:[0,1] neg_hi:[0,1]
	v_pk_add_f32 v[110:111], v[110:111], v[192:193] op_sel_hi:[1,0] neg_lo:[0,1] neg_hi:[0,1]
	v_pk_add_f32 v[64:65], v[64:65], v[192:193] op_sel_hi:[1,0] neg_lo:[0,1] neg_hi:[0,1]
	v_pk_add_f32 v[66:67], v[66:67], v[192:193] op_sel_hi:[1,0] neg_lo:[0,1] neg_hi:[0,1]
	v_pk_add_f32 v[68:69], v[68:69], v[192:193] op_sel_hi:[1,0] neg_lo:[0,1] neg_hi:[0,1]
	v_pk_add_f32 v[70:71], v[70:71], v[192:193] op_sel_hi:[1,0] neg_lo:[0,1] neg_hi:[0,1]
	v_pk_add_f32 v[72:73], v[72:73], v[192:193] op_sel_hi:[1,0] neg_lo:[0,1] neg_hi:[0,1]
	v_pk_add_f32 v[74:75], v[74:75], v[192:193] op_sel_hi:[1,0] neg_lo:[0,1] neg_hi:[0,1]
	v_pk_add_f32 v[76:77], v[76:77], v[192:193] op_sel_hi:[1,0] neg_lo:[0,1] neg_hi:[0,1]
	v_pk_add_f32 v[78:79], v[78:79], v[192:193] op_sel_hi:[1,0] neg_lo:[0,1] neg_hi:[0,1]
	v_mov_b32_e32 v193, v194
	v_pk_mul_f32 v[46:47], v[46:47], v[196:197] op_sel_hi:[1,0]
	v_pk_mul_f32 v[44:45], v[44:45], v[196:197] op_sel_hi:[1,0]
	v_pk_mul_f32 v[42:43], v[42:43], v[196:197] op_sel_hi:[1,0]
	v_pk_mul_f32 v[40:41], v[40:41], v[196:197] op_sel_hi:[1,0]
	v_pk_mul_f32 v[38:39], v[38:39], v[196:197] op_sel_hi:[1,0]
	v_pk_mul_f32 v[36:37], v[36:37], v[196:197] op_sel_hi:[1,0]
	v_pk_mul_f32 v[34:35], v[34:35], v[196:197] op_sel_hi:[1,0]
	v_pk_mul_f32 v[32:33], v[32:33], v[196:197] op_sel_hi:[1,0]
	v_pk_mul_f32 v[62:63], v[62:63], v[196:197] op_sel_hi:[1,0]
	v_pk_mul_f32 v[60:61], v[60:61], v[196:197] op_sel_hi:[1,0]
	v_pk_mul_f32 v[58:59], v[58:59], v[196:197] op_sel_hi:[1,0]
	v_pk_mul_f32 v[56:57], v[56:57], v[196:197] op_sel_hi:[1,0]
	v_pk_mul_f32 v[54:55], v[54:55], v[196:197] op_sel_hi:[1,0]
	v_pk_mul_f32 v[52:53], v[52:53], v[196:197] op_sel_hi:[1,0]
	v_pk_mul_f32 v[50:51], v[50:51], v[196:197] op_sel_hi:[1,0]
	v_pk_mul_f32 v[48:49], v[48:49], v[196:197] op_sel_hi:[1,0]
	v_pk_add_f32 v[112:113], v[112:113], v[194:195] op_sel_hi:[1,0] neg_lo:[0,1] neg_hi:[0,1]
	v_pk_add_f32 v[114:115], v[114:115], v[194:195] op_sel_hi:[1,0] neg_lo:[0,1] neg_hi:[0,1]
	v_pk_add_f32 v[116:117], v[116:117], v[194:195] op_sel_hi:[1,0] neg_lo:[0,1] neg_hi:[0,1]
	v_pk_add_f32 v[118:119], v[118:119], v[194:195] op_sel_hi:[1,0] neg_lo:[0,1] neg_hi:[0,1]
	v_pk_add_f32 v[120:121], v[120:121], v[194:195] op_sel_hi:[1,0] neg_lo:[0,1] neg_hi:[0,1]
	v_pk_add_f32 v[122:123], v[122:123], v[194:195] op_sel_hi:[1,0] neg_lo:[0,1] neg_hi:[0,1]
	v_pk_add_f32 v[124:125], v[124:125], v[194:195] op_sel_hi:[1,0] neg_lo:[0,1] neg_hi:[0,1]
	v_pk_add_f32 v[126:127], v[126:127], v[194:195] op_sel_hi:[1,0] neg_lo:[0,1] neg_hi:[0,1]
	v_pk_add_f32 v[80:81], v[80:81], v[194:195] op_sel_hi:[1,0] neg_lo:[0,1] neg_hi:[0,1]
	v_pk_add_f32 v[82:83], v[82:83], v[194:195] op_sel_hi:[1,0] neg_lo:[0,1] neg_hi:[0,1]
	v_pk_add_f32 v[84:85], v[84:85], v[194:195] op_sel_hi:[1,0] neg_lo:[0,1] neg_hi:[0,1]
	v_pk_add_f32 v[86:87], v[86:87], v[194:195] op_sel_hi:[1,0] neg_lo:[0,1] neg_hi:[0,1]
	v_pk_add_f32 v[88:89], v[88:89], v[194:195] op_sel_hi:[1,0] neg_lo:[0,1] neg_hi:[0,1]
	v_pk_add_f32 v[90:91], v[90:91], v[194:195] op_sel_hi:[1,0] neg_lo:[0,1] neg_hi:[0,1]
	v_pk_add_f32 v[92:93], v[92:93], v[194:195] op_sel_hi:[1,0] neg_lo:[0,1] neg_hi:[0,1]
	v_pk_add_f32 v[94:95], v[94:95], v[194:195] op_sel_hi:[1,0] neg_lo:[0,1] neg_hi:[0,1]
	v_pk_mul_f32 v[182:183], v[182:183], v[200:201]
	v_pk_add_f32 v[180:181], v[180:181], v[192:193]
	s_branch .LBB0_191
